# FFN1-out layer-0 epilogue (f32 residual x from HBM): rolling 7-step window of hoisted loads with counted vmcnt; passA NL column sums batched
# baseline (speedup 1.0000x reference)
.LBB0_229:
	v_lshl_add_u32 v148, s33, 8, v150
	v_lshl_or_b32 v146, s57, 8, v152
	v_ashrrev_i32_e32 v149, 31, v148
	v_ashrrev_i32_e32 v147, 31, v146
	v_lshlrev_b64 v[144:145], 11, v[148:149]
	v_lshl_add_u64 v[144:145], v[144:145], 0, v[146:147]
	v_lshl_add_u64 v[164:165], v[144:145], 2, s[8:9]
	v_mov_b32_e32 v242, v164
	v_mov_b32_e32 v243, v165
	global_load_dwordx4 v[168:171], v[242:243], off
	global_load_dwordx4 v[172:175], v[242:243], off offset:16
	global_load_dwordx4 v[176:179], v[242:243], off offset:512
	global_load_dwordx4 v[180:183], v[242:243], off offset:528
	s_mov_b64 s[98:99], 0x20000
	v_lshl_add_u64 v[244:245], v[242:243], 0, s[98:99]
	global_load_dwordx4 v[184:187], v[244:245], off
	global_load_dwordx4 v[188:191], v[244:245], off offset:16
	s_mov_b64 s[98:99], 0x20000
	v_lshl_add_u64 v[244:245], v[242:243], 0, s[98:99]
	global_load_dwordx4 v[192:195], v[244:245], off offset:512
	global_load_dwordx4 v[214:217], v[244:245], off offset:528
	s_mov_b64 s[98:99], 0x40000
	v_lshl_add_u64 v[244:245], v[242:243], 0, s[98:99]
	global_load_dwordx4 v[218:221], v[244:245], off
	global_load_dwordx4 v[222:225], v[244:245], off offset:16
	s_mov_b64 s[98:99], 0x40000
	v_lshl_add_u64 v[244:245], v[242:243], 0, s[98:99]
	global_load_dwordx4 v[226:229], v[244:245], off offset:512
	global_load_dwordx4 v[230:233], v[244:245], off offset:528
	s_mov_b64 s[98:99], 0x60000
	v_lshl_add_u64 v[244:245], v[242:243], 0, s[98:99]
	global_load_dwordx4 v[234:237], v[244:245], off
	global_load_dwordx4 v[238:241], v[244:245], off offset:16
	s_nop 1
	s_waitcnt vmcnt(12)
	v_mov_b32_e32 v156, v168
	v_mov_b32_e32 v157, v169
	v_mov_b32_e32 v158, v170
	v_mov_b32_e32 v159, v171
	s_nop 1
	v_mov_b32_e32 v160, v172
	v_mov_b32_e32 v161, v173
	v_mov_b32_e32 v162, v174
	v_mov_b32_e32 v163, v175
	s_mov_b64 s[98:99], 0x60000
	v_lshl_add_u64 v[244:245], v[242:243], 0, s[98:99]
	global_load_dwordx4 v[168:171], v[244:245], off offset:512
	global_load_dwordx4 v[172:175], v[244:245], off offset:528
	v_lshl_add_u64 v[166:167], v[144:145], 1, s[12:13]
	s_and_b64 vcc, exec, s[0:1]
	s_mov_b64 s[0:1], -1
	v_pk_mul_f32 v[156:157], v[156:157], s[18:19] op_sel_hi:[1,0]
	v_pk_mul_f32 v[162:163], v[162:163], s[18:19] op_sel_hi:[1,0]
	v_pk_mul_f32 v[160:161], v[160:161], s[18:19] op_sel_hi:[1,0]
	v_pk_mul_f32 v[158:159], v[158:159], s[18:19] op_sel_hi:[1,0]
	v_pk_fma_f32 v[124:125], v[124:125], 0.5, v[156:157] op_sel_hi:[1,0,1]
	v_pk_fma_f32 v[156:157], v[122:123], 0.5, v[162:163] op_sel_hi:[1,0,1]
	v_pk_fma_f32 v[122:123], v[120:121], 0.5, v[160:161] op_sel_hi:[1,0,1]
	v_pk_fma_f32 v[126:127], v[126:127], 0.5, v[158:159] op_sel_hi:[1,0,1]
	v_cvt_pk_bf16_f32 v120, v124, v125
	s_nop 0
	v_cvt_pk_bf16_f32 v121, v126, v127
	v_cvt_pk_bf16_f32 v122, v122, v123
	v_cvt_pk_bf16_f32 v123, v156, v157
	global_store_dwordx4 v[166:167], v[120:123], off
	s_nop 1
	s_waitcnt vmcnt(13)
	v_mov_b32_e32 v120, v176
	v_mov_b32_e32 v121, v177
	v_mov_b32_e32 v122, v178
	v_mov_b32_e32 v123, v179
	s_nop 0
	s_nop 1
	v_mov_b32_e32 v124, v180
	v_mov_b32_e32 v125, v181
	v_mov_b32_e32 v126, v182
	v_mov_b32_e32 v127, v183
	s_mov_b64 s[98:99], 0x100000
	v_lshl_add_u64 v[244:245], v[242:243], 0, s[98:99]
	global_load_dwordx4 v[176:179], v[244:245], off
	global_load_dwordx4 v[180:183], v[244:245], off offset:16
	v_or_b32_e32 v156, 16, v148
	v_ashrrev_i32_e32 v157, 31, v156
	v_lshlrev_b64 v[156:157], 11, v[156:157]
	v_lshl_add_u64 v[156:157], v[156:157], 0, v[146:147]
	v_lshl_add_u64 v[158:159], v[156:157], 2, s[8:9]
	v_pk_mul_f32 v[120:121], v[120:121], s[18:19] op_sel_hi:[1,0]
	v_pk_mul_f32 v[126:127], v[126:127], s[18:19] op_sel_hi:[1,0]
	v_pk_mul_f32 v[124:125], v[124:125], s[18:19] op_sel_hi:[1,0]
	v_pk_mul_f32 v[122:123], v[122:123], s[18:19] op_sel_hi:[1,0]
	v_pk_fma_f32 v[116:117], v[116:117], 0.5, v[120:121] op_sel_hi:[1,0,1]
	v_pk_fma_f32 v[120:121], v[114:115], 0.5, v[126:127] op_sel_hi:[1,0,1]
	v_pk_fma_f32 v[114:115], v[112:113], 0.5, v[124:125] op_sel_hi:[1,0,1]
	v_pk_fma_f32 v[118:119], v[118:119], 0.5, v[122:123] op_sel_hi:[1,0,1]
	v_cvt_pk_bf16_f32 v112, v116, v117
	s_nop 0
	v_cvt_pk_bf16_f32 v113, v118, v119
	v_cvt_pk_bf16_f32 v114, v114, v115
	v_cvt_pk_bf16_f32 v115, v120, v121
	global_store_dwordx4 v[166:167], v[112:115], off offset:256
	s_nop 1
	s_waitcnt vmcnt(14)
	v_mov_b32_e32 v112, v184
	v_mov_b32_e32 v113, v185
	v_mov_b32_e32 v114, v186
	v_mov_b32_e32 v115, v187
	s_nop 0
	s_nop 1
	v_mov_b32_e32 v116, v188
	v_mov_b32_e32 v117, v189
	v_mov_b32_e32 v118, v190
	v_mov_b32_e32 v119, v191
	s_mov_b64 s[98:99], 0x100000
	v_lshl_add_u64 v[244:245], v[242:243], 0, s[98:99]
	global_load_dwordx4 v[184:187], v[244:245], off offset:512
	global_load_dwordx4 v[188:191], v[244:245], off offset:528
	v_lshl_add_u64 v[120:121], v[156:157], 1, s[12:13]
	v_pk_mul_f32 v[112:113], v[112:113], s[18:19] op_sel_hi:[1,0]
	v_pk_mul_f32 v[118:119], v[118:119], s[18:19] op_sel_hi:[1,0]
	v_pk_mul_f32 v[116:117], v[116:117], s[18:19] op_sel_hi:[1,0]
	v_pk_mul_f32 v[114:115], v[114:115], s[18:19] op_sel_hi:[1,0]
	v_pk_fma_f32 v[108:109], v[108:109], 0.5, v[112:113] op_sel_hi:[1,0,1]
	v_pk_fma_f32 v[112:113], v[106:107], 0.5, v[118:119] op_sel_hi:[1,0,1]
	v_pk_fma_f32 v[106:107], v[104:105], 0.5, v[116:117] op_sel_hi:[1,0,1]
	v_pk_fma_f32 v[110:111], v[110:111], 0.5, v[114:115] op_sel_hi:[1,0,1]
	v_cvt_pk_bf16_f32 v104, v108, v109
	s_nop 0
	v_cvt_pk_bf16_f32 v105, v110, v111
	v_cvt_pk_bf16_f32 v106, v106, v107
	v_cvt_pk_bf16_f32 v107, v112, v113
	global_store_dwordx4 v[120:121], v[104:107], off
	s_nop 1
	s_waitcnt vmcnt(15)
	v_mov_b32_e32 v104, v192
	v_mov_b32_e32 v105, v193
	v_mov_b32_e32 v106, v194
	v_mov_b32_e32 v107, v195
	s_nop 0
	s_nop 1
	v_mov_b32_e32 v108, v214
	v_mov_b32_e32 v109, v215
	v_mov_b32_e32 v110, v216
	v_mov_b32_e32 v111, v217
	s_mov_b64 s[98:99], 0x120000
	v_lshl_add_u64 v[244:245], v[242:243], 0, s[98:99]
	global_load_dwordx4 v[192:195], v[244:245], off
	global_load_dwordx4 v[214:217], v[244:245], off offset:16
	v_or_b32_e32 v112, 32, v148
	v_ashrrev_i32_e32 v113, 31, v112
	v_lshlrev_b64 v[112:113], 11, v[112:113]
	v_lshl_add_u64 v[112:113], v[112:113], 0, v[146:147]
	v_lshl_add_u64 v[114:115], v[112:113], 2, s[8:9]
	v_pk_mul_f32 v[104:105], v[104:105], s[18:19] op_sel_hi:[1,0]
	v_pk_mul_f32 v[110:111], v[110:111], s[18:19] op_sel_hi:[1,0]
	v_pk_mul_f32 v[108:109], v[108:109], s[18:19] op_sel_hi:[1,0]
	v_pk_mul_f32 v[106:107], v[106:107], s[18:19] op_sel_hi:[1,0]
	v_pk_fma_f32 v[100:101], v[100:101], 0.5, v[104:105] op_sel_hi:[1,0,1]
	v_pk_fma_f32 v[104:105], v[98:99], 0.5, v[110:111] op_sel_hi:[1,0,1]
	v_pk_fma_f32 v[98:99], v[96:97], 0.5, v[108:109] op_sel_hi:[1,0,1]
	v_pk_fma_f32 v[102:103], v[102:103], 0.5, v[106:107] op_sel_hi:[1,0,1]
	v_cvt_pk_bf16_f32 v96, v100, v101
	s_nop 0
	v_cvt_pk_bf16_f32 v97, v102, v103
	v_cvt_pk_bf16_f32 v98, v98, v99
	v_cvt_pk_bf16_f32 v99, v104, v105
	global_store_dwordx4 v[120:121], v[96:99], off offset:256
	s_nop 1
	s_waitcnt vmcnt(16)
	v_mov_b32_e32 v96, v218
	v_mov_b32_e32 v97, v219
	v_mov_b32_e32 v98, v220
	v_mov_b32_e32 v99, v221
	s_nop 0
	s_nop 1
	v_mov_b32_e32 v100, v222
	v_mov_b32_e32 v101, v223
	v_mov_b32_e32 v102, v224
	v_mov_b32_e32 v103, v225
	s_mov_b64 s[98:99], 0x120000
	v_lshl_add_u64 v[244:245], v[242:243], 0, s[98:99]
	global_load_dwordx4 v[218:221], v[244:245], off offset:512
	global_load_dwordx4 v[222:225], v[244:245], off offset:528
	v_lshl_add_u64 v[104:105], v[112:113], 1, s[12:13]
	v_pk_mul_f32 v[96:97], v[96:97], s[18:19] op_sel_hi:[1,0]
	v_pk_mul_f32 v[102:103], v[102:103], s[18:19] op_sel_hi:[1,0]
	v_pk_mul_f32 v[100:101], v[100:101], s[18:19] op_sel_hi:[1,0]
	v_pk_mul_f32 v[98:99], v[98:99], s[18:19] op_sel_hi:[1,0]
	v_pk_fma_f32 v[92:93], v[92:93], 0.5, v[96:97] op_sel_hi:[1,0,1]
	v_pk_fma_f32 v[96:97], v[90:91], 0.5, v[102:103] op_sel_hi:[1,0,1]
	v_pk_fma_f32 v[90:91], v[88:89], 0.5, v[100:101] op_sel_hi:[1,0,1]
	v_pk_fma_f32 v[94:95], v[94:95], 0.5, v[98:99] op_sel_hi:[1,0,1]
	v_cvt_pk_bf16_f32 v88, v92, v93
	s_nop 0
	v_cvt_pk_bf16_f32 v89, v94, v95
	v_cvt_pk_bf16_f32 v90, v90, v91
	v_cvt_pk_bf16_f32 v91, v96, v97
	global_store_dwordx4 v[104:105], v[88:91], off
	s_nop 1
	s_waitcnt vmcnt(17)
	v_mov_b32_e32 v88, v226
	v_mov_b32_e32 v89, v227
	v_mov_b32_e32 v90, v228
	v_mov_b32_e32 v91, v229
	s_nop 0
	s_nop 1
	v_mov_b32_e32 v92, v230
	v_mov_b32_e32 v93, v231
	v_mov_b32_e32 v94, v232
	v_mov_b32_e32 v95, v233
	s_mov_b64 s[98:99], 0x140000
	v_lshl_add_u64 v[244:245], v[242:243], 0, s[98:99]
	global_load_dwordx4 v[226:229], v[244:245], off
	global_load_dwordx4 v[230:233], v[244:245], off offset:16
	v_or_b32_e32 v96, 48, v148
	v_ashrrev_i32_e32 v97, 31, v96
	v_lshlrev_b64 v[96:97], 11, v[96:97]
	v_lshl_add_u64 v[96:97], v[96:97], 0, v[146:147]
	v_lshl_add_u64 v[98:99], v[96:97], 2, s[8:9]
	v_pk_mul_f32 v[88:89], v[88:89], s[18:19] op_sel_hi:[1,0]
	v_pk_mul_f32 v[94:95], v[94:95], s[18:19] op_sel_hi:[1,0]
	v_pk_mul_f32 v[92:93], v[92:93], s[18:19] op_sel_hi:[1,0]
	v_pk_mul_f32 v[90:91], v[90:91], s[18:19] op_sel_hi:[1,0]
	v_pk_fma_f32 v[84:85], v[84:85], 0.5, v[88:89] op_sel_hi:[1,0,1]
	v_pk_fma_f32 v[88:89], v[82:83], 0.5, v[94:95] op_sel_hi:[1,0,1]
	v_pk_fma_f32 v[82:83], v[80:81], 0.5, v[92:93] op_sel_hi:[1,0,1]
	v_pk_fma_f32 v[86:87], v[86:87], 0.5, v[90:91] op_sel_hi:[1,0,1]
	v_cvt_pk_bf16_f32 v80, v84, v85
	s_nop 0
	v_cvt_pk_bf16_f32 v81, v86, v87
	v_cvt_pk_bf16_f32 v82, v82, v83
	v_cvt_pk_bf16_f32 v83, v88, v89
	global_store_dwordx4 v[104:105], v[80:83], off offset:256
	s_nop 1
	s_waitcnt vmcnt(18)
	v_mov_b32_e32 v80, v234
	v_mov_b32_e32 v81, v235
	v_mov_b32_e32 v82, v236
	v_mov_b32_e32 v83, v237
	s_nop 0
	s_nop 1
	v_mov_b32_e32 v84, v238
	v_mov_b32_e32 v85, v239
	v_mov_b32_e32 v86, v240
	v_mov_b32_e32 v87, v241
	s_mov_b64 s[98:99], 0x140000
	v_lshl_add_u64 v[244:245], v[242:243], 0, s[98:99]
	global_load_dwordx4 v[234:237], v[244:245], off offset:512
	global_load_dwordx4 v[238:241], v[244:245], off offset:528
	v_lshl_add_u64 v[88:89], v[96:97], 1, s[12:13]
	v_pk_mul_f32 v[80:81], v[80:81], s[18:19] op_sel_hi:[1,0]
	v_pk_mul_f32 v[86:87], v[86:87], s[18:19] op_sel_hi:[1,0]
	v_pk_mul_f32 v[84:85], v[84:85], s[18:19] op_sel_hi:[1,0]
	v_pk_mul_f32 v[82:83], v[82:83], s[18:19] op_sel_hi:[1,0]
	v_pk_fma_f32 v[76:77], v[76:77], 0.5, v[80:81] op_sel_hi:[1,0,1]
	v_pk_fma_f32 v[80:81], v[74:75], 0.5, v[86:87] op_sel_hi:[1,0,1]
	v_pk_fma_f32 v[74:75], v[72:73], 0.5, v[84:85] op_sel_hi:[1,0,1]
	v_pk_fma_f32 v[78:79], v[78:79], 0.5, v[82:83] op_sel_hi:[1,0,1]
	v_cvt_pk_bf16_f32 v72, v76, v77
	s_nop 0
	v_cvt_pk_bf16_f32 v73, v78, v79
	v_cvt_pk_bf16_f32 v74, v74, v75
	v_cvt_pk_bf16_f32 v75, v80, v81
	global_store_dwordx4 v[88:89], v[72:75], off
	s_nop 1
	s_waitcnt vmcnt(19)
	v_mov_b32_e32 v72, v168
	v_mov_b32_e32 v73, v169
	v_mov_b32_e32 v74, v170
	v_mov_b32_e32 v75, v171
	s_nop 0
	s_nop 1
	v_mov_b32_e32 v76, v172
	v_mov_b32_e32 v77, v173
	v_mov_b32_e32 v78, v174
	v_mov_b32_e32 v79, v175
	s_mov_b64 s[98:99], 0x160000
	v_lshl_add_u64 v[244:245], v[242:243], 0, s[98:99]
	global_load_dwordx4 v[168:171], v[244:245], off
	global_load_dwordx4 v[172:175], v[244:245], off offset:16
	v_lshl_add_u64 v[80:81], v[144:145], 0, s[20:21]
	v_lshl_add_u64 v[82:83], v[80:81], 2, s[8:9]
	v_pk_mul_f32 v[72:73], v[72:73], s[18:19] op_sel_hi:[1,0]
	v_pk_mul_f32 v[78:79], v[78:79], s[18:19] op_sel_hi:[1,0]
	v_pk_mul_f32 v[76:77], v[76:77], s[18:19] op_sel_hi:[1,0]
	v_pk_mul_f32 v[74:75], v[74:75], s[18:19] op_sel_hi:[1,0]
	v_pk_fma_f32 v[68:69], v[68:69], 0.5, v[72:73] op_sel_hi:[1,0,1]
	v_pk_fma_f32 v[72:73], v[66:67], 0.5, v[78:79] op_sel_hi:[1,0,1]
	v_pk_fma_f32 v[66:67], v[64:65], 0.5, v[76:77] op_sel_hi:[1,0,1]
	v_pk_fma_f32 v[70:71], v[70:71], 0.5, v[74:75] op_sel_hi:[1,0,1]
	v_cvt_pk_bf16_f32 v64, v68, v69
	s_nop 0
	v_cvt_pk_bf16_f32 v65, v70, v71
	v_cvt_pk_bf16_f32 v66, v66, v67
	v_cvt_pk_bf16_f32 v67, v72, v73
	global_store_dwordx4 v[88:89], v[64:67], off offset:256
	s_nop 1
	s_waitcnt vmcnt(19)
	v_mov_b32_e32 v64, v176
	v_mov_b32_e32 v65, v177
	v_mov_b32_e32 v66, v178
	v_mov_b32_e32 v67, v179
	s_nop 0
	s_nop 1
	v_mov_b32_e32 v68, v180
	v_mov_b32_e32 v69, v181
	v_mov_b32_e32 v70, v182
	v_mov_b32_e32 v71, v183
	s_mov_b64 s[98:99], 0x160000
	v_lshl_add_u64 v[244:245], v[242:243], 0, s[98:99]
	global_load_dwordx4 v[176:179], v[244:245], off offset:512
	global_load_dwordx4 v[180:183], v[244:245], off offset:528
	v_lshl_add_u64 v[72:73], v[80:81], 1, s[12:13]
	v_pk_mul_f32 v[64:65], v[64:65], s[18:19] op_sel_hi:[1,0]
	v_pk_mul_f32 v[70:71], v[70:71], s[18:19] op_sel_hi:[1,0]
	v_pk_mul_f32 v[68:69], v[68:69], s[18:19] op_sel_hi:[1,0]
	v_pk_mul_f32 v[66:67], v[66:67], s[18:19] op_sel_hi:[1,0]
	v_pk_fma_f32 v[60:61], v[60:61], 0.5, v[64:65] op_sel_hi:[1,0,1]
	v_pk_fma_f32 v[64:65], v[58:59], 0.5, v[70:71] op_sel_hi:[1,0,1]
	v_pk_fma_f32 v[58:59], v[56:57], 0.5, v[68:69] op_sel_hi:[1,0,1]
	v_pk_fma_f32 v[62:63], v[62:63], 0.5, v[66:67] op_sel_hi:[1,0,1]
	v_cvt_pk_bf16_f32 v56, v60, v61
	s_nop 0
	v_cvt_pk_bf16_f32 v57, v62, v63
	v_cvt_pk_bf16_f32 v58, v58, v59
	v_cvt_pk_bf16_f32 v59, v64, v65
	global_store_dwordx4 v[72:73], v[56:59], off
	s_nop 1
	s_waitcnt vmcnt(19)
	v_mov_b32_e32 v56, v184
	v_mov_b32_e32 v57, v185
	v_mov_b32_e32 v58, v186
	v_mov_b32_e32 v59, v187
	s_nop 0
	s_nop 1
	v_mov_b32_e32 v60, v188
	v_mov_b32_e32 v61, v189
	v_mov_b32_e32 v62, v190
	v_mov_b32_e32 v63, v191
	v_lshl_add_u64 v[64:65], v[144:145], 0, s[22:23]
	v_lshl_add_u64 v[66:67], v[64:65], 2, s[8:9]
	v_pk_mul_f32 v[56:57], v[56:57], s[18:19] op_sel_hi:[1,0]
	v_pk_mul_f32 v[62:63], v[62:63], s[18:19] op_sel_hi:[1,0]
	v_pk_mul_f32 v[60:61], v[60:61], s[18:19] op_sel_hi:[1,0]
	v_pk_mul_f32 v[58:59], v[58:59], s[18:19] op_sel_hi:[1,0]
	v_pk_fma_f32 v[52:53], v[52:53], 0.5, v[56:57] op_sel_hi:[1,0,1]
	v_pk_fma_f32 v[56:57], v[50:51], 0.5, v[62:63] op_sel_hi:[1,0,1]
	v_pk_fma_f32 v[50:51], v[48:49], 0.5, v[60:61] op_sel_hi:[1,0,1]
	v_pk_fma_f32 v[54:55], v[54:55], 0.5, v[58:59] op_sel_hi:[1,0,1]
	v_cvt_pk_bf16_f32 v48, v52, v53
	s_nop 0
	v_cvt_pk_bf16_f32 v49, v54, v55
	v_cvt_pk_bf16_f32 v50, v50, v51
	v_cvt_pk_bf16_f32 v51, v56, v57
	global_store_dwordx4 v[72:73], v[48:51], off offset:256
	s_nop 1
	s_waitcnt vmcnt(17)
	v_mov_b32_e32 v48, v192
	v_mov_b32_e32 v49, v193
	v_mov_b32_e32 v50, v194
	v_mov_b32_e32 v51, v195
	s_nop 0
	s_nop 1
	v_mov_b32_e32 v52, v214
	v_mov_b32_e32 v53, v215
	v_mov_b32_e32 v54, v216
	v_mov_b32_e32 v55, v217
	v_lshl_add_u64 v[56:57], v[64:65], 1, s[12:13]
	v_pk_mul_f32 v[48:49], v[48:49], s[18:19] op_sel_hi:[1,0]
	v_pk_mul_f32 v[54:55], v[54:55], s[18:19] op_sel_hi:[1,0]
	v_pk_mul_f32 v[52:53], v[52:53], s[18:19] op_sel_hi:[1,0]
	v_pk_mul_f32 v[50:51], v[50:51], s[18:19] op_sel_hi:[1,0]
	v_pk_fma_f32 v[44:45], v[44:45], 0.5, v[48:49] op_sel_hi:[1,0,1]
	v_pk_fma_f32 v[48:49], v[42:43], 0.5, v[54:55] op_sel_hi:[1,0,1]
	v_pk_fma_f32 v[42:43], v[40:41], 0.5, v[52:53] op_sel_hi:[1,0,1]
	v_pk_fma_f32 v[46:47], v[46:47], 0.5, v[50:51] op_sel_hi:[1,0,1]
	v_cvt_pk_bf16_f32 v40, v44, v45
	s_nop 0
	v_cvt_pk_bf16_f32 v41, v46, v47
	v_cvt_pk_bf16_f32 v42, v42, v43
	v_cvt_pk_bf16_f32 v43, v48, v49
	global_store_dwordx4 v[56:57], v[40:43], off
	s_nop 1
	s_waitcnt vmcnt(15)
	v_mov_b32_e32 v40, v218
	v_mov_b32_e32 v41, v219
	v_mov_b32_e32 v42, v220
	v_mov_b32_e32 v43, v221
	s_nop 0
	s_nop 1
	v_mov_b32_e32 v44, v222
	v_mov_b32_e32 v45, v223
	v_mov_b32_e32 v46, v224
	v_mov_b32_e32 v47, v225
	v_lshl_add_u64 v[48:49], v[144:145], 0, s[24:25]
	v_lshl_add_u64 v[50:51], v[48:49], 2, s[8:9]
	v_pk_mul_f32 v[40:41], v[40:41], s[18:19] op_sel_hi:[1,0]
	v_pk_mul_f32 v[46:47], v[46:47], s[18:19] op_sel_hi:[1,0]
	v_pk_mul_f32 v[44:45], v[44:45], s[18:19] op_sel_hi:[1,0]
	v_pk_mul_f32 v[42:43], v[42:43], s[18:19] op_sel_hi:[1,0]
	v_pk_fma_f32 v[36:37], v[36:37], 0.5, v[40:41] op_sel_hi:[1,0,1]
	v_pk_fma_f32 v[40:41], v[34:35], 0.5, v[46:47] op_sel_hi:[1,0,1]
	v_pk_fma_f32 v[34:35], v[32:33], 0.5, v[44:45] op_sel_hi:[1,0,1]
	v_pk_fma_f32 v[38:39], v[38:39], 0.5, v[42:43] op_sel_hi:[1,0,1]
	v_cvt_pk_bf16_f32 v32, v36, v37
	s_nop 0
	v_cvt_pk_bf16_f32 v33, v38, v39
	v_cvt_pk_bf16_f32 v34, v34, v35
	v_cvt_pk_bf16_f32 v35, v40, v41
	global_store_dwordx4 v[56:57], v[32:35], off offset:256
	s_nop 1
	s_waitcnt vmcnt(13)
	v_mov_b32_e32 v32, v226
	v_mov_b32_e32 v33, v227
	v_mov_b32_e32 v34, v228
	v_mov_b32_e32 v35, v229
	s_nop 0
	s_nop 1
	v_mov_b32_e32 v36, v230
	v_mov_b32_e32 v37, v231
	v_mov_b32_e32 v38, v232
	v_mov_b32_e32 v39, v233
	v_lshl_add_u64 v[40:41], v[48:49], 1, s[12:13]
	v_pk_mul_f32 v[32:33], v[32:33], s[18:19] op_sel_hi:[1,0]
	v_pk_mul_f32 v[38:39], v[38:39], s[18:19] op_sel_hi:[1,0]
	v_pk_mul_f32 v[36:37], v[36:37], s[18:19] op_sel_hi:[1,0]
	v_pk_mul_f32 v[34:35], v[34:35], s[18:19] op_sel_hi:[1,0]
	v_pk_fma_f32 v[28:29], v[28:29], 0.5, v[32:33] op_sel_hi:[1,0,1]
	v_pk_fma_f32 v[32:33], v[26:27], 0.5, v[38:39] op_sel_hi:[1,0,1]
	v_pk_fma_f32 v[26:27], v[24:25], 0.5, v[36:37] op_sel_hi:[1,0,1]
	v_pk_fma_f32 v[30:31], v[30:31], 0.5, v[34:35] op_sel_hi:[1,0,1]
	v_cvt_pk_bf16_f32 v24, v28, v29
	s_nop 0
	v_cvt_pk_bf16_f32 v25, v30, v31
	v_cvt_pk_bf16_f32 v26, v26, v27
	v_cvt_pk_bf16_f32 v27, v32, v33
	global_store_dwordx4 v[40:41], v[24:27], off
	s_nop 1
	s_waitcnt vmcnt(11)
	v_mov_b32_e32 v24, v234
	v_mov_b32_e32 v25, v235
	v_mov_b32_e32 v26, v236
	v_mov_b32_e32 v27, v237
	s_nop 0
	s_nop 1
	v_mov_b32_e32 v28, v238
	v_mov_b32_e32 v29, v239
	v_mov_b32_e32 v30, v240
	v_mov_b32_e32 v31, v241
	v_lshl_add_u64 v[32:33], v[144:145], 0, s[26:27]
	v_lshl_add_u64 v[34:35], v[32:33], 2, s[8:9]
	v_pk_mul_f32 v[24:25], v[24:25], s[18:19] op_sel_hi:[1,0]
	v_pk_mul_f32 v[30:31], v[30:31], s[18:19] op_sel_hi:[1,0]
	v_pk_mul_f32 v[28:29], v[28:29], s[18:19] op_sel_hi:[1,0]
	v_pk_mul_f32 v[26:27], v[26:27], s[18:19] op_sel_hi:[1,0]
	v_pk_fma_f32 v[20:21], v[20:21], 0.5, v[24:25] op_sel_hi:[1,0,1]
	v_pk_fma_f32 v[24:25], v[18:19], 0.5, v[30:31] op_sel_hi:[1,0,1]
	v_pk_fma_f32 v[18:19], v[16:17], 0.5, v[28:29] op_sel_hi:[1,0,1]
	v_pk_fma_f32 v[22:23], v[22:23], 0.5, v[26:27] op_sel_hi:[1,0,1]
	v_cvt_pk_bf16_f32 v16, v20, v21
	s_nop 0
	v_cvt_pk_bf16_f32 v17, v22, v23
	v_cvt_pk_bf16_f32 v18, v18, v19
	v_cvt_pk_bf16_f32 v19, v24, v25
	global_store_dwordx4 v[40:41], v[16:19], off offset:256
	s_nop 1
	s_waitcnt vmcnt(9)
	v_mov_b32_e32 v16, v168
	v_mov_b32_e32 v17, v169
	v_mov_b32_e32 v18, v170
	v_mov_b32_e32 v19, v171
	s_nop 0
	s_nop 1
	v_mov_b32_e32 v20, v172
	v_mov_b32_e32 v21, v173
	v_mov_b32_e32 v22, v174
	v_mov_b32_e32 v23, v175
	v_lshl_add_u64 v[24:25], v[32:33], 1, s[12:13]
	v_pk_mul_f32 v[16:17], v[16:17], s[18:19] op_sel_hi:[1,0]
	v_pk_mul_f32 v[22:23], v[22:23], s[18:19] op_sel_hi:[1,0]
	v_pk_mul_f32 v[20:21], v[20:21], s[18:19] op_sel_hi:[1,0]
	v_pk_mul_f32 v[18:19], v[18:19], s[18:19] op_sel_hi:[1,0]
	v_pk_fma_f32 v[12:13], v[12:13], 0.5, v[16:17] op_sel_hi:[1,0,1]
	v_pk_fma_f32 v[16:17], v[10:11], 0.5, v[22:23] op_sel_hi:[1,0,1]
	v_pk_fma_f32 v[10:11], v[8:9], 0.5, v[20:21] op_sel_hi:[1,0,1]
	v_pk_fma_f32 v[14:15], v[14:15], 0.5, v[18:19] op_sel_hi:[1,0,1]
	v_cvt_pk_bf16_f32 v8, v12, v13
	s_nop 0
	v_cvt_pk_bf16_f32 v9, v14, v15
	v_cvt_pk_bf16_f32 v10, v10, v11
	v_cvt_pk_bf16_f32 v11, v16, v17
	global_store_dwordx4 v[24:25], v[8:11], off
	s_nop 1
	s_waitcnt vmcnt(7)
	v_mov_b32_e32 v8, v176
	v_mov_b32_e32 v9, v177
	v_mov_b32_e32 v10, v178
	v_mov_b32_e32 v11, v179
	s_nop 0
	s_nop 1
	v_mov_b32_e32 v12, v180
	v_mov_b32_e32 v13, v181
	v_mov_b32_e32 v14, v182
	v_mov_b32_e32 v15, v183
	v_pk_mul_f32 v[8:9], v[8:9], s[18:19] op_sel_hi:[1,0]
	v_pk_mul_f32 v[14:15], v[14:15], s[18:19] op_sel_hi:[1,0]
	v_pk_mul_f32 v[12:13], v[12:13], s[18:19] op_sel_hi:[1,0]
	v_pk_mul_f32 v[10:11], v[10:11], s[18:19] op_sel_hi:[1,0]
	v_pk_fma_f32 v[4:5], v[4:5], 0.5, v[8:9] op_sel_hi:[1,0,1]
	v_pk_fma_f32 v[8:9], v[2:3], 0.5, v[14:15] op_sel_hi:[1,0,1]
	v_pk_fma_f32 v[2:3], v[0:1], 0.5, v[12:13] op_sel_hi:[1,0,1]
	v_pk_fma_f32 v[6:7], v[6:7], 0.5, v[10:11] op_sel_hi:[1,0,1]
	v_cvt_pk_bf16_f32 v0, v4, v5
	s_nop 0
	v_cvt_pk_bf16_f32 v1, v6, v7
	v_cvt_pk_bf16_f32 v2, v2, v3
	v_cvt_pk_bf16_f32 v3, v8, v9
	global_store_dwordx4 v[24:25], v[0:3], off offset:256
	s_cbranch_vccnz .LBB0_214
	s_andn2_b64 vcc, exec, s[10:11]
	s_cbranch_vccnz .LBB0_213
	s_barrier
	s_branch .LBB0_213

.LBB0_557:
	ds_read_u16 v112, v19
	ds_read_u16 v113, v19 offset:272
	ds_read_u16 v114, v19 offset:544
	ds_read_u16 v115, v19 offset:816
	ds_read_u16 v116, v19 offset:1088
	ds_read_u16 v117, v19 offset:1360
	ds_read_u16 v118, v19 offset:1632
	ds_read_u16 v119, v19 offset:1904
	ds_read_u16 v120, v19 offset:2176
	ds_read_u16 v121, v19 offset:2448
	ds_read_u16 v122, v19 offset:2720
	ds_read_u16 v123, v19 offset:2992
	ds_read_u16 v124, v19 offset:3264
	ds_read_u16 v125, v19 offset:3536
	ds_read_u16 v126, v19 offset:3808
	ds_read_u16 v127, v19 offset:4080
	ds_read_u16 v128, v19 offset:4352
	ds_read_u16 v129, v19 offset:4624
	ds_read_u16 v130, v19 offset:4896
	ds_read_u16 v131, v19 offset:5168
	ds_read_u16 v132, v19 offset:5440
	ds_read_u16 v133, v19 offset:5712
	ds_read_u16 v134, v19 offset:5984
	ds_read_u16 v135, v19 offset:6256
	ds_read_u16 v136, v19 offset:6528
	ds_read_u16 v137, v19 offset:6800
	ds_read_u16 v138, v19 offset:7072
	ds_read_u16 v139, v19 offset:7344
	ds_read_u16 v140, v19 offset:7616
	ds_read_u16 v141, v19 offset:7888
	ds_read_u16 v142, v19 offset:8160
	ds_read_u16 v143, v19 offset:8432
	ds_read_u16 v144, v19 offset:8704
	ds_read_u16 v145, v19 offset:8976
	ds_read_u16 v146, v19 offset:9248
	ds_read_u16 v147, v19 offset:9520
	ds_read_u16 v148, v19 offset:9792
	ds_read_u16 v149, v19 offset:10064
	ds_read_u16 v150, v19 offset:10336
	ds_read_u16 v151, v19 offset:10608
	ds_read_u16 v152, v19 offset:10880
	ds_read_u16 v153, v19 offset:11152
	ds_read_u16 v154, v19 offset:11424
	ds_read_u16 v155, v19 offset:11696
	ds_read_u16 v156, v19 offset:11968
	ds_read_u16 v157, v19 offset:12240
	ds_read_u16 v158, v19 offset:12512
	ds_read_u16 v159, v19 offset:12784
	ds_read_u16 v160, v19 offset:13056
	ds_read_u16 v161, v19 offset:13328
	ds_read_u16 v162, v19 offset:13600
	ds_read_u16 v163, v19 offset:13872
	ds_read_u16 v164, v19 offset:14144
	ds_read_u16 v165, v19 offset:14416
	ds_read_u16 v166, v19 offset:14688
	ds_read_u16 v167, v19 offset:14960
	ds_read_u16 v168, v19 offset:15232
	ds_read_u16 v169, v19 offset:15504
	ds_read_u16 v170, v19 offset:15776
	ds_read_u16 v171, v19 offset:16048
	ds_read_u16 v172, v19 offset:16320
	ds_read_u16 v173, v19 offset:16592
	ds_read_u16 v174, v19 offset:16864
	ds_read_u16 v175, v19 offset:17136
	s_waitcnt lgkmcnt(0)
	v_lshlrev_b32_e32 v112, 16, v112
	v_add_f32_e32 v24, v24, v112
	v_lshlrev_b32_e32 v113, 16, v113
	v_add_f32_e32 v24, v24, v113
	v_lshlrev_b32_e32 v114, 16, v114
	v_add_f32_e32 v24, v24, v114
	v_lshlrev_b32_e32 v115, 16, v115
	v_add_f32_e32 v24, v24, v115
	v_lshlrev_b32_e32 v116, 16, v116
	v_add_f32_e32 v24, v24, v116
	v_lshlrev_b32_e32 v117, 16, v117
	v_add_f32_e32 v24, v24, v117
	v_lshlrev_b32_e32 v118, 16, v118
	v_add_f32_e32 v24, v24, v118
	v_lshlrev_b32_e32 v119, 16, v119
	v_add_f32_e32 v24, v24, v119
	v_lshlrev_b32_e32 v120, 16, v120
	v_add_f32_e32 v24, v24, v120
	v_lshlrev_b32_e32 v121, 16, v121
	v_add_f32_e32 v24, v24, v121
	v_lshlrev_b32_e32 v122, 16, v122
	v_add_f32_e32 v24, v24, v122
	v_lshlrev_b32_e32 v123, 16, v123
	v_add_f32_e32 v24, v24, v123
	v_lshlrev_b32_e32 v124, 16, v124
	v_add_f32_e32 v24, v24, v124
	v_lshlrev_b32_e32 v125, 16, v125
	v_add_f32_e32 v24, v24, v125
	v_lshlrev_b32_e32 v126, 16, v126
	v_add_f32_e32 v24, v24, v126
	v_lshlrev_b32_e32 v127, 16, v127
	v_add_f32_e32 v24, v24, v127
	v_lshlrev_b32_e32 v128, 16, v128
	v_add_f32_e32 v24, v24, v128
	v_lshlrev_b32_e32 v129, 16, v129
	v_add_f32_e32 v24, v24, v129
	v_lshlrev_b32_e32 v130, 16, v130
	v_add_f32_e32 v24, v24, v130
	v_lshlrev_b32_e32 v131, 16, v131
	v_add_f32_e32 v24, v24, v131
	v_lshlrev_b32_e32 v132, 16, v132
	v_add_f32_e32 v24, v24, v132
	v_lshlrev_b32_e32 v133, 16, v133
	v_add_f32_e32 v24, v24, v133
	v_lshlrev_b32_e32 v134, 16, v134
	v_add_f32_e32 v24, v24, v134
	v_lshlrev_b32_e32 v135, 16, v135
	v_add_f32_e32 v24, v24, v135
	v_lshlrev_b32_e32 v136, 16, v136
	v_add_f32_e32 v24, v24, v136
	v_lshlrev_b32_e32 v137, 16, v137
	v_add_f32_e32 v24, v24, v137
	v_lshlrev_b32_e32 v138, 16, v138
	v_add_f32_e32 v24, v24, v138
	v_lshlrev_b32_e32 v139, 16, v139
	v_add_f32_e32 v24, v24, v139
	v_lshlrev_b32_e32 v140, 16, v140
	v_add_f32_e32 v24, v24, v140
	v_lshlrev_b32_e32 v141, 16, v141
	v_add_f32_e32 v24, v24, v141
	v_lshlrev_b32_e32 v142, 16, v142
	v_add_f32_e32 v24, v24, v142
	v_lshlrev_b32_e32 v143, 16, v143
	v_add_f32_e32 v24, v24, v143
	v_lshlrev_b32_e32 v144, 16, v144
	v_add_f32_e32 v24, v24, v144
	v_lshlrev_b32_e32 v145, 16, v145
	v_add_f32_e32 v24, v24, v145
	v_lshlrev_b32_e32 v146, 16, v146
	v_add_f32_e32 v24, v24, v146
	v_lshlrev_b32_e32 v147, 16, v147
	v_add_f32_e32 v24, v24, v147
	v_lshlrev_b32_e32 v148, 16, v148
	v_add_f32_e32 v24, v24, v148
	v_lshlrev_b32_e32 v149, 16, v149
	v_add_f32_e32 v24, v24, v149
	v_lshlrev_b32_e32 v150, 16, v150
	v_add_f32_e32 v24, v24, v150
	v_lshlrev_b32_e32 v151, 16, v151
	v_add_f32_e32 v24, v24, v151
	v_lshlrev_b32_e32 v152, 16, v152
	v_add_f32_e32 v24, v24, v152
	v_lshlrev_b32_e32 v153, 16, v153
	v_add_f32_e32 v24, v24, v153
	v_lshlrev_b32_e32 v154, 16, v154
	v_add_f32_e32 v24, v24, v154
	v_lshlrev_b32_e32 v155, 16, v155
	v_add_f32_e32 v24, v24, v155
	v_lshlrev_b32_e32 v156, 16, v156
	v_add_f32_e32 v24, v24, v156
	v_lshlrev_b32_e32 v157, 16, v157
	v_add_f32_e32 v24, v24, v157
	v_lshlrev_b32_e32 v158, 16, v158
	v_add_f32_e32 v24, v24, v158
	v_lshlrev_b32_e32 v159, 16, v159
	v_add_f32_e32 v24, v24, v159
	v_lshlrev_b32_e32 v160, 16, v160
	v_add_f32_e32 v24, v24, v160
	v_lshlrev_b32_e32 v161, 16, v161
	v_add_f32_e32 v24, v24, v161
	v_lshlrev_b32_e32 v162, 16, v162
	v_add_f32_e32 v24, v24, v162
	v_lshlrev_b32_e32 v163, 16, v163
	v_add_f32_e32 v24, v24, v163
	v_lshlrev_b32_e32 v164, 16, v164
	v_add_f32_e32 v24, v24, v164
	v_lshlrev_b32_e32 v165, 16, v165
	v_add_f32_e32 v24, v24, v165
	v_lshlrev_b32_e32 v166, 16, v166
	v_add_f32_e32 v24, v24, v166
	v_lshlrev_b32_e32 v167, 16, v167
	v_add_f32_e32 v24, v24, v167
	v_lshlrev_b32_e32 v168, 16, v168
	v_add_f32_e32 v24, v24, v168
	v_lshlrev_b32_e32 v169, 16, v169
	v_add_f32_e32 v24, v24, v169
	v_lshlrev_b32_e32 v170, 16, v170
	v_add_f32_e32 v24, v24, v170
	v_lshlrev_b32_e32 v171, 16, v171
	v_add_f32_e32 v24, v24, v171
	v_lshlrev_b32_e32 v172, 16, v172
	v_add_f32_e32 v24, v24, v172
	v_lshlrev_b32_e32 v173, 16, v173
	v_add_f32_e32 v24, v24, v173
	v_lshlrev_b32_e32 v174, 16, v174
	v_add_f32_e32 v24, v24, v174
	v_lshlrev_b32_e32 v175, 16, v175
	v_add_f32_e32 v24, v24, v175
	s_lshl_b64 s[20:21], s[18:19], 9
	v_lshl_add_u64 v[26:27], v[10:11], 0, s[20:21]
	global_store_dword v[26:27], v24, off
	s_branch .LBB0_552
